# rescale sites: inline full wait between the masked factor ds_write and the four factor ds_reads dropped (one wave's DS ops execute in issue order); on top of v_all6
# baseline (speedup 1.0000x reference)
; #define LAS __attribute__((address_space(3)))
; template <int MODE>
; __device__ __forceinline__ void att_tile(LAS unsigned char* lds, int buf, int kv0, int wq0, int r32, int hi, int mapi, const bf16x8 (&qr)[4], f32x16 (&O)[AttCfg<MODE>::NC], float& mrun, float& lsum, LAS float* wsf, bool fixed = false  ) {
;     ...
;     if (!fixed) {
;     if (__any(alpha != 1.0f)) {
;         if (hi == 0) wsf[r32] = alpha;
;         asm volatile("s_waitcnt lgkmcnt(0)" ::: "memory");
; #pragma unroll
;         for (int i = 0; i < 4; ++i) { const f32x4 av = *(const LAS f32x4*)(wsf + 8 * i + 4 * hi);
; #pragma unroll
;             for (int c = 0; c < NC; ++c)
; #pragma unroll
;                 for (int k = 0; k < 4; ++k) O[c][4 * i + k] *= av[k]; }
;         asm volatile("s_waitcnt lgkmcnt(0)" ::: "memory");
;     }
.LBB0_258:
	s_andn2_b64 vcc, exec, s[50:51]
	s_cbranch_vccnz .LBB0_263
	v_cmp_neq_f32_e32 vcc, 1.0, v239
	s_cbranch_vccz .LBB0_263
	s_and_saveexec_b64 s[10:11], s[40:41]
	ds_write_b32 v217, v239
	s_or_b64 exec, exec, s[10:11]
	ds_read_b128 v[242:245], v216 offset:96
	ds_read_b128 v[246:249], v216 offset:64
	ds_read_b128 v[200:203], v216 offset:32
	ds_read_b128 v[222:225], v216
	s_waitcnt lgkmcnt(3)
	v_pk_mul_f32 v[64:65], v[64:65], v[244:245]
	v_pk_mul_f32 v[62:63], v[62:63], v[242:243]
	v_pk_mul_f32 v[48:49], v[48:49], v[244:245]
	v_pk_mul_f32 v[46:47], v[46:47], v[242:243]
	s_waitcnt lgkmcnt(2)
	v_pk_mul_f32 v[60:61], v[60:61], v[248:249]
	v_pk_mul_f32 v[58:59], v[58:59], v[246:247]
	v_pk_mul_f32 v[44:45], v[44:45], v[248:249]
	v_pk_mul_f32 v[42:43], v[42:43], v[246:247]
	s_waitcnt lgkmcnt(1)
	v_pk_mul_f32 v[56:57], v[56:57], v[202:203]
	v_pk_mul_f32 v[54:55], v[54:55], v[200:201]
	v_pk_mul_f32 v[40:41], v[40:41], v[202:203]
	v_pk_mul_f32 v[38:39], v[38:39], v[200:201]
	s_waitcnt lgkmcnt(0)
	v_pk_mul_f32 v[52:53], v[52:53], v[224:225]
	v_pk_mul_f32 v[50:51], v[50:51], v[222:223]
	v_pk_mul_f32 v[36:37], v[36:37], v[224:225]
	v_pk_mul_f32 v[34:35], v[34:35], v[222:223]
	v_pk_mul_f32 v[32:33], v[32:33], v[244:245]
	v_pk_mul_f32 v[28:29], v[28:29], v[248:249]
	v_pk_mul_f32 v[24:25], v[24:25], v[202:203]
	v_pk_mul_f32 v[20:21], v[20:21], v[224:225]
	v_pk_mul_f32 v[30:31], v[30:31], v[242:243]
	v_pk_mul_f32 v[26:27], v[26:27], v[246:247]
	v_pk_mul_f32 v[22:23], v[22:23], v[200:201]
	v_pk_mul_f32 v[18:19], v[18:19], v[222:223]
	v_pk_mul_f32 v[16:17], v[16:17], v[244:245]
	v_pk_mul_f32 v[12:13], v[12:13], v[248:249]
	v_pk_mul_f32 v[8:9], v[8:9], v[202:203]
	v_pk_mul_f32 v[4:5], v[4:5], v[224:225]
	v_pk_mul_f32 v[14:15], v[14:15], v[242:243]
	v_pk_mul_f32 v[10:11], v[10:11], v[246:247]
	v_pk_mul_f32 v[6:7], v[6:7], v[200:201]
	v_pk_mul_f32 v[2:3], v[2:3], v[222:223]

; #define LAS __attribute__((address_space(3)))
; template <int MODE>
; __device__ __forceinline__ void att_tile(LAS unsigned char* lds, int buf, int kv0, int wq0, int r32, int hi, int mapi, const bf16x8 (&qr)[4], f32x16 (&O)[AttCfg<MODE>::NC], float& mrun, float& lsum, LAS float* wsf, bool fixed = false  ) {
;     ...
;     if (!fixed) {
;     if (__any(alpha != 1.0f)) {
;         if (hi == 0) wsf[r32] = alpha;
;         asm volatile("s_waitcnt lgkmcnt(0)" ::: "memory");
; #pragma unroll
;         for (int i = 0; i < 4; ++i) { const f32x4 av = *(const LAS f32x4*)(wsf + 8 * i + 4 * hi);
; #pragma unroll
;             for (int c = 0; c < NC; ++c)
; #pragma unroll
;                 for (int k = 0; k < 4; ++k) O[c][4 * i + k] *= av[k]; }
;         asm volatile("s_waitcnt lgkmcnt(0)" ::: "memory");
;     }
.LBB0_285:
	s_andn2_b64 vcc, exec, s[50:51]
	s_cbranch_vccnz .LBB0_290
	v_cmp_neq_f32_e32 vcc, 1.0, v239
	s_cbranch_vccz .LBB0_290
	s_and_saveexec_b64 s[10:11], s[40:41]
	ds_write_b32 v217, v239
	s_or_b64 exec, exec, s[10:11]
	ds_read_b128 v[200:203], v216 offset:96
	ds_read_b128 v[222:225], v216 offset:64
	ds_read_b128 v[242:245], v216 offset:32
	ds_read_b128 v[246:249], v216
	s_waitcnt lgkmcnt(3)
	v_pk_mul_f32 v[64:65], v[64:65], v[202:203]
	v_pk_mul_f32 v[62:63], v[62:63], v[200:201]
	v_pk_mul_f32 v[48:49], v[48:49], v[202:203]
	v_pk_mul_f32 v[46:47], v[46:47], v[200:201]
	s_waitcnt lgkmcnt(2)
	v_pk_mul_f32 v[60:61], v[60:61], v[224:225]
	v_pk_mul_f32 v[58:59], v[58:59], v[222:223]
	v_pk_mul_f32 v[44:45], v[44:45], v[224:225]
	v_pk_mul_f32 v[42:43], v[42:43], v[222:223]
	s_waitcnt lgkmcnt(1)
	v_pk_mul_f32 v[56:57], v[56:57], v[244:245]
	v_pk_mul_f32 v[54:55], v[54:55], v[242:243]
	v_pk_mul_f32 v[40:41], v[40:41], v[244:245]
	v_pk_mul_f32 v[38:39], v[38:39], v[242:243]
	s_waitcnt lgkmcnt(0)
	v_pk_mul_f32 v[52:53], v[52:53], v[248:249]
	v_pk_mul_f32 v[50:51], v[50:51], v[246:247]
	v_pk_mul_f32 v[36:37], v[36:37], v[248:249]
	v_pk_mul_f32 v[34:35], v[34:35], v[246:247]
	v_pk_mul_f32 v[32:33], v[32:33], v[202:203]
	v_pk_mul_f32 v[28:29], v[28:29], v[224:225]
	v_pk_mul_f32 v[24:25], v[24:25], v[244:245]
	v_pk_mul_f32 v[20:21], v[20:21], v[248:249]
	v_pk_mul_f32 v[30:31], v[30:31], v[200:201]
	v_pk_mul_f32 v[26:27], v[26:27], v[222:223]
	v_pk_mul_f32 v[22:23], v[22:23], v[242:243]
	v_pk_mul_f32 v[18:19], v[18:19], v[246:247]
	v_pk_mul_f32 v[16:17], v[16:17], v[202:203]
	v_pk_mul_f32 v[12:13], v[12:13], v[224:225]
	v_pk_mul_f32 v[8:9], v[8:9], v[244:245]
	v_pk_mul_f32 v[4:5], v[4:5], v[248:249]
	v_pk_mul_f32 v[14:15], v[14:15], v[200:201]
	v_pk_mul_f32 v[10:11], v[10:11], v[222:223]
	v_pk_mul_f32 v[6:7], v[6:7], v[242:243]
	v_pk_mul_f32 v[2:3], v[2:3], v[246:247]

; #define LAS __attribute__((address_space(3)))
; template <int MODE>
; __device__ __forceinline__ void att_tile(LAS unsigned char* lds, int buf, int kv0, int wq0, int r32, int hi, int mapi, const bf16x8 (&qr)[4], f32x16 (&O)[AttCfg<MODE>::NC], float& mrun, float& lsum, LAS float* wsf, bool fixed = false  ) {
;     ...
;     if (!fixed) {
;     if (__any(alpha != 1.0f)) {
;         if (hi == 0) wsf[r32] = alpha;
;         asm volatile("s_waitcnt lgkmcnt(0)" ::: "memory");
; #pragma unroll
;         for (int i = 0; i < 4; ++i) { const f32x4 av = *(const LAS f32x4*)(wsf + 8 * i + 4 * hi);
; #pragma unroll
;             for (int c = 0; c < NC; ++c)
; #pragma unroll
;                 for (int k = 0; k < 4; ++k) O[c][4 * i + k] *= av[k]; }
;         asm volatile("s_waitcnt lgkmcnt(0)" ::: "memory");
;     }
.LBB0_348:
	s_andn2_b64 vcc, exec, s[8:9]
	s_cbranch_vccnz .LBB0_353
	v_cmp_neq_f32_e32 vcc, 1.0, v122
	s_cbranch_vccz .LBB0_353
	s_and_saveexec_b64 s[14:15], s[38:39]
	ds_write_b32 v140, v122
	s_or_b64 exec, exec, s[14:15]
	ds_read_b128 v[154:157], v139 offset:96
	ds_read_b128 v[158:161], v139 offset:64
	ds_read_b128 v[162:165], v139 offset:32
	ds_read_b128 v[166:169], v139
	s_waitcnt lgkmcnt(3)
	v_pk_mul_f32 v[32:33], v[32:33], v[156:157]
	v_pk_mul_f32 v[16:17], v[16:17], v[156:157]
	v_pk_mul_f32 v[30:31], v[30:31], v[154:155]
	v_pk_mul_f32 v[14:15], v[14:15], v[154:155]
	s_waitcnt lgkmcnt(2)
	v_pk_mul_f32 v[28:29], v[28:29], v[160:161]
	v_pk_mul_f32 v[12:13], v[12:13], v[160:161]
	v_pk_mul_f32 v[26:27], v[26:27], v[158:159]
	v_pk_mul_f32 v[10:11], v[10:11], v[158:159]
	s_waitcnt lgkmcnt(1)
	v_pk_mul_f32 v[24:25], v[24:25], v[164:165]
	v_pk_mul_f32 v[8:9], v[8:9], v[164:165]
	v_pk_mul_f32 v[22:23], v[22:23], v[162:163]
	v_pk_mul_f32 v[6:7], v[6:7], v[162:163]
	s_waitcnt lgkmcnt(0)
	v_pk_mul_f32 v[20:21], v[20:21], v[168:169]
	v_pk_mul_f32 v[4:5], v[4:5], v[168:169]
	v_pk_mul_f32 v[18:19], v[18:19], v[166:167]
	v_pk_mul_f32 v[2:3], v[2:3], v[166:167]

; #define LAS __attribute__((address_space(3)))
; __device__ __forceinline__ float xhalf_max(float v) { auto rr = __builtin_amdgcn_permlane32_swap(__float_as_uint(v), __float_as_uint(v), false, false); return fmaxf(__uint_as_float(rr[0]), __uint_as_float(rr[1])); }
; template <int MODE>
; __device__ __forceinline__ void att_tile(LAS unsigned char* lds, int buf, int kv0, int wq0, int r32, int hi, int mapi, const bf16x8 (&qr)[4], f32x16 (&O)[AttCfg<MODE>::NC], float& mrun, float& lsum, LAS float* wsf, bool fixed = false  ) {
;     ...
;     if (!fixed) {
;         float mxa = __builtin_fmaxf(p0[0], p0[1]), mxb = __builtin_fmaxf(p1[0], p1[1]);
; #pragma unroll
;         for (int r = 2; r < 16; r += 2) { mxa = __builtin_fmaxf(__builtin_fmaxf(mxa, p0[r]), p0[r + 1]); mxb = __builtin_fmaxf(__builtin_fmaxf(mxb, p1[r]), p1[r + 1]); }
;         float mx = __builtin_fmaxf(mxa, mxb);
;         mx = xhalf_max(mx);
;         const float mnew = fmaxf(mrun, mx); msafe = (mnew == NEG) ? 0.f : mnew;
;         alpha = __builtin_amdgcn_exp2f(mrun - msafe); mrun = mnew;
;     }
;     float ps = 0.f;
; #pragma unroll
;     for (int r = 0; r < 16; ++r) { p0[r] = __builtin_amdgcn_exp2f(p0[r] - msafe); p1[r] = __builtin_amdgcn_exp2f(p1[r] - msafe); ps += p0[r] + p1[r]; }
;     lsum = lsum * alpha + ps;
;     if (!fixed) {
;     if (__any(alpha != 1.0f)) {
;         if (hi == 0) wsf[r32] = alpha;
;         asm volatile("s_waitcnt lgkmcnt(0)" ::: "memory");
; #pragma unroll
;         for (int i = 0; i < 4; ++i) { const f32x4 av = *(const LAS f32x4*)(wsf + 8 * i + 4 * hi);
; #pragma unroll
;             for (int c = 0; c < NC; ++c)
; #pragma unroll
;                 for (int k = 0; k < 4; ++k) O[c][4 * i + k] *= av[k]; }
;         asm volatile("s_waitcnt lgkmcnt(0)" ::: "memory");
;     }
.LBB0_415:
	s_nop 4
	v_max_f32_e32 v139, v35, v35
	v_max_f32_e32 v142, v34, v34
	v_max_f32_e32 v139, v142, v139
	v_max3_f32 v142, v50, v51, v52
	v_max3_f32 v139, v139, v36, v37
	v_max3_f32 v142, v142, v53, v54
	v_max3_f32 v139, v139, v38, v39
	v_max3_f32 v142, v142, v55, v56
	v_max3_f32 v139, v139, v40, v41
	v_max3_f32 v142, v142, v57, v58
	v_max3_f32 v139, v139, v42, v43
	v_max3_f32 v142, v142, v59, v60
	v_max3_f32 v139, v139, v44, v45
	v_max3_f32 v142, v142, v61, v62
	v_max3_f32 v139, v139, v46, v47
	v_max3_f32 v142, v142, v63, v64
	v_max3_f32 v139, v139, v48, v49
	v_max3_f32 v139, v142, v65, v139
	v_mov_b32_e32 v142, v139
	s_nop 1
	v_permlane32_swap_b32_e32 v139, v142
	v_max3_f32 v139, v138, v139, v142
	v_cmp_neq_f32_e32 vcc, s66, v139
	s_nop 1
	v_cndmask_b32_e32 v142, 0, v139, vcc
	v_sub_f32_e32 v138, v138, v142
	v_exp_f32_e32 v138, v138
	s_nop 0
	v_cmp_neq_f32_e32 vcc, 1.0, v138
	s_cbranch_vccz .LBB0_419
	s_and_saveexec_b64 s[10:11], s[36:37]
	ds_write_b32 v122, v138
	s_or_b64 exec, exec, s[10:11]
	ds_read_b128 v[144:147], v131 offset:96
	ds_read_b128 v[148:151], v131 offset:64
	ds_read_b128 v[152:155], v131 offset:32
	ds_read_b128 v[156:159], v131
	s_waitcnt lgkmcnt(3)
	v_pk_mul_f32 v[16:17], v[16:17], v[146:147]
	v_pk_mul_f32 v[32:33], v[32:33], v[146:147]
	v_pk_mul_f32 v[14:15], v[14:15], v[144:145]
	v_pk_mul_f32 v[30:31], v[30:31], v[144:145]
	s_waitcnt lgkmcnt(2)
	v_pk_mul_f32 v[12:13], v[12:13], v[150:151]
	v_pk_mul_f32 v[28:29], v[28:29], v[150:151]
	v_pk_mul_f32 v[10:11], v[10:11], v[148:149]
	v_pk_mul_f32 v[26:27], v[26:27], v[148:149]
	s_waitcnt lgkmcnt(1)
	v_pk_mul_f32 v[8:9], v[8:9], v[154:155]
	v_pk_mul_f32 v[24:25], v[24:25], v[154:155]
	v_pk_mul_f32 v[6:7], v[6:7], v[152:153]
	v_pk_mul_f32 v[22:23], v[22:23], v[152:153]
	s_waitcnt lgkmcnt(0)
	v_pk_mul_f32 v[4:5], v[4:5], v[158:159]
	v_pk_mul_f32 v[20:21], v[20:21], v[158:159]
	v_pk_mul_f32 v[2:3], v[2:3], v[156:157]
	v_pk_mul_f32 v[18:19], v[18:19], v[156:157]

; #define LAS __attribute__((address_space(3)))
; __device__ __forceinline__ float xhalf_max(float v) { auto rr = __builtin_amdgcn_permlane32_swap(__float_as_uint(v), __float_as_uint(v), false, false); return fmaxf(__uint_as_float(rr[0]), __uint_as_float(rr[1])); }
; template <int MODE>
; __device__ __forceinline__ void att_tile(LAS unsigned char* lds, int buf, int kv0, int wq0, int r32, int hi, int mapi, const bf16x8 (&qr)[4], f32x16 (&O)[AttCfg<MODE>::NC], float& mrun, float& lsum, LAS float* wsf, bool fixed = false  ) {
;     ...
;     if (!fixed) {
;         float mxa = __builtin_fmaxf(p0[0], p0[1]), mxb = __builtin_fmaxf(p1[0], p1[1]);
; #pragma unroll
;         for (int r = 2; r < 16; r += 2) { mxa = __builtin_fmaxf(__builtin_fmaxf(mxa, p0[r]), p0[r + 1]); mxb = __builtin_fmaxf(__builtin_fmaxf(mxb, p1[r]), p1[r + 1]); }
;         float mx = __builtin_fmaxf(mxa, mxb);
;         mx = xhalf_max(mx);
;         const float mnew = fmaxf(mrun, mx); msafe = (mnew == NEG) ? 0.f : mnew;
;         alpha = __builtin_amdgcn_exp2f(mrun - msafe); mrun = mnew;
;     }
;     float ps = 0.f;
; #pragma unroll
;     for (int r = 0; r < 16; ++r) { p0[r] = __builtin_amdgcn_exp2f(p0[r] - msafe); p1[r] = __builtin_amdgcn_exp2f(p1[r] - msafe); ps += p0[r] + p1[r]; }
;     lsum = lsum * alpha + ps;
;     if (!fixed) {
;     if (__any(alpha != 1.0f)) {
;         if (hi == 0) wsf[r32] = alpha;
;         asm volatile("s_waitcnt lgkmcnt(0)" ::: "memory");
; #pragma unroll
;         for (int i = 0; i < 4; ++i) { const f32x4 av = *(const LAS f32x4*)(wsf + 8 * i + 4 * hi);
; #pragma unroll
;             for (int c = 0; c < NC; ++c)
; #pragma unroll
;                 for (int k = 0; k < 4; ++k) O[c][4 * i + k] *= av[k]; }
;         asm volatile("s_waitcnt lgkmcnt(0)" ::: "memory");
;     }
.LBB0_430:
	s_nop 4
	v_max_f32_e32 v138, v35, v35
	v_max_f32_e32 v142, v34, v34
	v_max_f32_e32 v138, v142, v138
	v_max3_f32 v142, v50, v51, v52
	v_max3_f32 v138, v138, v36, v37
	v_max3_f32 v142, v142, v53, v54
	v_max3_f32 v138, v138, v38, v39
	v_max3_f32 v142, v142, v55, v56
	v_max3_f32 v138, v138, v40, v41
	v_max3_f32 v142, v142, v57, v58
	v_max3_f32 v138, v138, v42, v43
	v_max3_f32 v142, v142, v59, v60
	v_max3_f32 v138, v138, v44, v45
	v_max3_f32 v142, v142, v61, v62
	v_max3_f32 v138, v138, v46, v47
	v_max3_f32 v142, v142, v63, v64
	v_max3_f32 v138, v138, v48, v49
	v_max3_f32 v138, v142, v65, v138
	v_mov_b32_e32 v142, v138
	s_nop 1
	v_permlane32_swap_b32_e32 v138, v142
	v_max3_f32 v138, v139, v138, v142
	v_cmp_neq_f32_e32 vcc, s66, v138
	s_nop 1
	v_cndmask_b32_e32 v142, 0, v138, vcc
	v_sub_f32_e32 v139, v139, v142
	v_exp_f32_e32 v139, v139
	s_nop 0
	v_cmp_neq_f32_e32 vcc, 1.0, v139
	s_cbranch_vccz .LBB0_434
	s_and_saveexec_b64 s[10:11], s[36:37]
	ds_write_b32 v122, v139
	s_or_b64 exec, exec, s[10:11]
	ds_read_b128 v[144:147], v131 offset:96
	ds_read_b128 v[148:151], v131 offset:64
	ds_read_b128 v[152:155], v131 offset:32
	ds_read_b128 v[156:159], v131
	s_waitcnt lgkmcnt(3)
	v_pk_mul_f32 v[16:17], v[16:17], v[146:147]
	v_pk_mul_f32 v[32:33], v[32:33], v[146:147]
	v_pk_mul_f32 v[14:15], v[14:15], v[144:145]
	v_pk_mul_f32 v[30:31], v[30:31], v[144:145]
	s_waitcnt lgkmcnt(2)
	v_pk_mul_f32 v[12:13], v[12:13], v[150:151]
	v_pk_mul_f32 v[28:29], v[28:29], v[150:151]
	v_pk_mul_f32 v[10:11], v[10:11], v[148:149]
	v_pk_mul_f32 v[26:27], v[26:27], v[148:149]
	s_waitcnt lgkmcnt(1)
	v_pk_mul_f32 v[8:9], v[8:9], v[154:155]
	v_pk_mul_f32 v[24:25], v[24:25], v[154:155]
	v_pk_mul_f32 v[6:7], v[6:7], v[152:153]
	v_pk_mul_f32 v[22:23], v[22:23], v[152:153]
	s_waitcnt lgkmcnt(0)
	v_pk_mul_f32 v[4:5], v[4:5], v[158:159]
	v_pk_mul_f32 v[20:21], v[20:21], v[158:159]
	v_pk_mul_f32 v[2:3], v[2:3], v[156:157]
	v_pk_mul_f32 v[18:19], v[18:19], v[156:157]
